# T2: SEL/WIN/CMP1 no score-init copy; SEL/WIN/fox scalar-base tile loads (on T1)
# speedup vs baseline: 1.0570x; 1.0139x over previous
.LBB0_658:
	s_or_b64 exec, exec, s[0:1]
	v_mov_b32_e32 v14, v1
	v_mov_b32_e32 v15, v1
	v_lshlrev_b32_e32 v143, 3, v25
	s_lshl_b32 s8, s15, 1
	v_lshlrev_b32_e32 v141, 2, v25
	v_mul_u32_u24_e32 v144, 0x90, v24
	v_mul_u32_u24_e32 v145, 0x88, v24
	v_lshl_add_u64 v[132:133], s[4:5], 0, v[0:1]
	v_lshl_add_u64 v[134:135], v[22:23], 2, s[6:7]
	v_add_u32_e32 v146, 0x80, v20
	v_add_u32_e32 v147, 0x80, v18
	s_mov_b32 s86, 0
	v_mov_b32_e32 v0, v1
	v_mov_b32_e32 v2, v1
	v_mov_b32_e32 v3, v1
	v_mov_b32_e32 v4, v1
	v_mov_b32_e32 v5, v1
	v_mov_b32_e32 v6, v1
	v_mov_b32_e32 v7, v1
	v_mov_b32_e32 v8, v1
	v_mov_b32_e32 v9, v1
	v_mov_b32_e32 v10, v1
	v_mov_b32_e32 v11, v1
	v_mov_b32_e32 v12, v1
	v_mov_b32_e32 v13, v1
	v_mov_b64_e32 v[30:31], v[14:15]
	v_mov_b64_e32 v[46:47], v[14:15]
	s_add_i32 s9, s8, 2
	s_or_b32 s15, s16, 31
	v_mov_b32_e32 v136, 0x42000000
	v_mov_b32_e32 v148, 0xc2000000
	v_mov_b32_e32 v142, 0
	v_mov_b64_e32 v[28:29], v[12:13]
	v_mov_b64_e32 v[26:27], v[10:11]
	v_mov_b64_e32 v[24:25], v[8:9]
	v_mov_b64_e32 v[22:23], v[6:7]
	v_mov_b64_e32 v[20:21], v[4:5]
	v_mov_b64_e32 v[18:19], v[2:3]
	v_mov_b64_e32 v[16:17], v[0:1]
	v_mov_b64_e32 v[44:45], v[12:13]
	v_mov_b64_e32 v[42:43], v[10:11]
	v_mov_b64_e32 v[40:41], v[8:9]
	v_mov_b64_e32 v[38:39], v[6:7]
	v_mov_b64_e32 v[36:37], v[4:5]
	v_mov_b64_e32 v[34:35], v[2:3]
	v_mov_b64_e32 v[32:33], v[0:1]
	s_mov_b32 s6, s86
	s_mov_b32 s7, s86
	s_and_b32 s18, s13, 7
	s_lshl_b32 s17, s18, 20
	s_lshl_b32 s18, s18, 15
	s_add_u32 s10, s58, s17
	s_addc_u32 s11, s59, 0
	s_add_u32 s22, s54, s17
	s_addc_u32 s23, s55, 0
	s_add_u32 s24, s53, s18
	s_addc_u32 s25, s61, 0
	s_add_u32 s10, s10, 0x4000
	s_addc_u32 s11, s11, 0
	s_add_u32 s22, s22, 0x100
	s_addc_u32 s23, s23, 0
	s_add_u32 s24, s24, 0x200
	s_addc_u32 s25, s25, 0
	v_lshlrev_b32_e32 v228, 4, v156
	v_lshrrev_b32_e32 v230, 3, v156
	v_and_b32_e32 v231, 7, v156
	v_add_u32_e32 v229, 0x1000, v228
	v_lshlrev_b32_e32 v230, 14, v230
	v_lshl_add_u32 v230, v231, 4, v230
	v_add_u32_e32 v231, 0x80000, v230

.LBB0_663:
	s_cmp_ge_u32 s7, s8
	s_cbranch_scc1 .LBB0_667
	global_load_dwordx4 v[100:103], v228, s[10:11]
	global_load_dwordx4 v[104:107], v230, s[22:23]
	global_load_dwordx4 v[108:111], v229, s[10:11]
	global_load_dwordx4 v[112:115], v231, s[22:23]
	s_and_saveexec_b64 s[0:1], s[38:39]
	s_cbranch_execz .LBB0_666
	global_load_dwordx4 v[96:99], v228, s[24:25]
.LBB0_666:
	s_or_b64 exec, exec, s[0:1]
	s_add_u32 s10, s10, 0x2000
	s_addc_u32 s11, s11, 0
	s_add_u32 s22, s22, 0x80
	s_addc_u32 s23, s23, 0
	s_add_u32 s24, s24, 0x100
	s_addc_u32 s25, s25, 0

.LBB0_775:
	s_cmp_gt_i32 s17, s16
	s_waitcnt lgkmcnt(0)
	s_barrier
	s_cbranch_scc1 .LBB0_782
	s_mulk_i32 s4, 0x4a00
	v_add_u32_e32 v76, s4, v71
	ds_read_b128 v[18:21], v76
	ds_read_b128 v[72:75], v76 offset:4608
	s_add_i32 s4, s22, 63
	v_cmp_le_i32_e32 vcc, s4, v198
	s_cmp_eq_u64 vcc, exec
	s_waitcnt lgkmcnt(1)
	v_mfma_f32_32x32x16_bf16 v[34:49], v[18:21], v[82:85], v[2:17]
	s_waitcnt lgkmcnt(0)
	v_mfma_f32_32x32x16_bf16 v[18:33], v[72:75], v[82:85], v[2:17]
	ds_read_b128 v[72:75], v76 offset:32
	s_waitcnt lgkmcnt(0)
	v_mfma_f32_32x32x16_bf16 v[34:49], v[72:75], v[86:89], v[34:49]
	ds_read_b128 v[72:75], v76 offset:4640
	s_waitcnt lgkmcnt(0)
	v_mfma_f32_32x32x16_bf16 v[18:33], v[72:75], v[86:89], v[18:33]
	ds_read_b128 v[72:75], v76 offset:64
	s_waitcnt lgkmcnt(0)
	v_mfma_f32_32x32x16_bf16 v[34:49], v[72:75], v[90:93], v[34:49]
	ds_read_b128 v[72:75], v76 offset:4672
	s_waitcnt lgkmcnt(0)
	v_mfma_f32_32x32x16_bf16 v[18:33], v[72:75], v[90:93], v[18:33]
	ds_read_b128 v[72:75], v76 offset:96
	s_waitcnt lgkmcnt(0)
	v_mfma_f32_32x32x16_bf16 v[34:49], v[72:75], v[94:97], v[34:49]
	ds_read_b128 v[72:75], v76 offset:4704
	s_waitcnt lgkmcnt(0)
	v_mfma_f32_32x32x16_bf16 v[18:33], v[72:75], v[94:97], v[18:33]
	s_cbranch_scc1 .LBB0_780
	v_add_u32_e32 v72, s22, v125
	v_cmp_lt_i32_e32 vcc, v72, v198
	v_add_u32_e32 v73, 2, v72
	s_nop 4
	v_cndmask_b32_e32 v35, v169, v35, vcc
	v_cmp_le_i32_e32 vcc, v72, v198
	s_nop 1
	v_cndmask_b32_e32 v34, v169, v34, vcc
	v_cmp_le_i32_e32 vcc, v73, v198
	v_add_u32_e32 v73, 3, v72
	s_nop 0
	v_cndmask_b32_e32 v36, v169, v36, vcc
	v_cmp_le_i32_e32 vcc, v73, v198
	v_add_u32_e32 v73, 8, v72
	s_nop 0
	v_cndmask_b32_e32 v37, v169, v37, vcc
	v_cmp_le_i32_e32 vcc, v73, v198
	v_add_u32_e32 v73, 9, v72
	s_nop 0
	v_cndmask_b32_e32 v38, v169, v38, vcc
	v_cmp_le_i32_e32 vcc, v73, v198
	v_add_u32_e32 v73, 10, v72
	s_nop 0
	v_cndmask_b32_e32 v39, v169, v39, vcc
	v_cmp_le_i32_e32 vcc, v73, v198
	v_add_u32_e32 v73, 11, v72
	s_nop 0
	v_cndmask_b32_e32 v40, v169, v40, vcc
	v_cmp_le_i32_e32 vcc, v73, v198
	v_add_u32_e32 v73, 16, v72
	s_nop 0
	v_cndmask_b32_e32 v41, v169, v41, vcc
	v_cmp_le_i32_e32 vcc, v73, v198
	v_add_u32_e32 v73, 17, v72
	s_nop 0
	v_cndmask_b32_e32 v42, v169, v42, vcc
	v_cmp_le_i32_e32 vcc, v73, v198
	v_add_u32_e32 v73, 18, v72
	s_nop 0
	v_cndmask_b32_e32 v43, v169, v43, vcc
	v_cmp_le_i32_e32 vcc, v73, v198
	v_add_u32_e32 v73, 19, v72
	s_nop 0
	v_cndmask_b32_e32 v44, v169, v44, vcc
	v_cmp_le_i32_e32 vcc, v73, v198
	v_add_u32_e32 v73, 24, v72
	s_nop 0
	v_cndmask_b32_e32 v45, v169, v45, vcc
	v_cmp_le_i32_e32 vcc, v73, v198
	v_add_u32_e32 v73, 25, v72
	s_nop 0
	v_cndmask_b32_e32 v46, v169, v46, vcc
	v_cmp_le_i32_e32 vcc, v73, v198
	v_add_u32_e32 v73, 26, v72
	s_nop 0
	v_cndmask_b32_e32 v47, v169, v47, vcc
	v_cmp_le_i32_e32 vcc, v73, v198
	v_add_u32_e32 v73, 27, v72
	s_nop 0
	v_cndmask_b32_e32 v48, v169, v48, vcc
	v_cmp_le_i32_e32 vcc, v73, v198
	v_add_u32_e32 v73, 32, v72
	s_nop 0
	v_cndmask_b32_e32 v49, v169, v49, vcc
	v_cmp_le_i32_e32 vcc, v73, v198
	v_add_u32_e32 v73, 33, v72
	s_nop 0
	v_cndmask_b32_e32 v18, v169, v18, vcc
	v_cmp_le_i32_e32 vcc, v73, v198
	v_add_u32_e32 v73, 34, v72
	s_nop 0
	v_cndmask_b32_e32 v19, v169, v19, vcc
	v_cmp_le_i32_e32 vcc, v73, v198
	v_add_u32_e32 v73, 35, v72
	s_nop 0
	v_cndmask_b32_e32 v20, v169, v20, vcc
	v_cmp_le_i32_e32 vcc, v73, v198
	v_add_u32_e32 v73, 40, v72
	s_nop 0
	v_cndmask_b32_e32 v21, v169, v21, vcc
	v_cmp_le_i32_e32 vcc, v73, v198
	v_add_u32_e32 v73, 41, v72
	s_nop 0
	v_cndmask_b32_e32 v22, v169, v22, vcc
	v_cmp_le_i32_e32 vcc, v73, v198
	v_add_u32_e32 v73, 42, v72
	s_nop 0
	v_cndmask_b32_e32 v23, v169, v23, vcc
	v_cmp_le_i32_e32 vcc, v73, v198
	v_add_u32_e32 v73, 43, v72
	s_nop 0
	v_cndmask_b32_e32 v24, v169, v24, vcc
	v_cmp_le_i32_e32 vcc, v73, v198
	v_add_u32_e32 v73, 48, v72
	s_nop 0
	v_cndmask_b32_e32 v25, v169, v25, vcc
	v_cmp_le_i32_e32 vcc, v73, v198
	v_add_u32_e32 v73, 49, v72
	s_nop 0
	v_cndmask_b32_e32 v26, v169, v26, vcc
	v_cmp_le_i32_e32 vcc, v73, v198
	v_add_u32_e32 v73, 50, v72
	s_nop 0
	v_cndmask_b32_e32 v27, v169, v27, vcc
	v_cmp_le_i32_e32 vcc, v73, v198
	v_add_u32_e32 v73, 51, v72
	s_nop 0
	v_cndmask_b32_e32 v28, v169, v28, vcc
	v_cmp_le_i32_e32 vcc, v73, v198
	v_add_u32_e32 v73, 56, v72
	s_nop 0
	v_cndmask_b32_e32 v29, v169, v29, vcc
	v_cmp_le_i32_e32 vcc, v73, v198
	v_add_u32_e32 v73, 57, v72
	s_nop 0
	v_cndmask_b32_e32 v30, v169, v30, vcc
	v_cmp_le_i32_e32 vcc, v73, v198
	v_add_u32_e32 v73, 58, v72
	v_add_u32_e32 v72, 59, v72
	v_cndmask_b32_e32 v31, v169, v31, vcc
	v_cmp_le_i32_e32 vcc, v73, v198
	s_nop 1
	v_cndmask_b32_e32 v32, v169, v32, vcc
	v_cmp_gt_i32_e32 vcc, v72, v198
	s_and_saveexec_b64 s[4:5], vcc
	v_mov_b32_e32 v33, 0xf149f2ca
	s_or_b64 exec, exec, s[4:5]

.LBB0_904:
	v_mov_b32_e32 v16, v1
	v_mov_b32_e32 v17, v1
	v_mov_b32_e32 v2, v1
	v_mov_b32_e32 v3, v1
	v_mov_b32_e32 v4, v1
	v_mov_b32_e32 v5, v1
	v_mov_b32_e32 v6, v1
	v_mov_b32_e32 v7, v1
	v_mov_b32_e32 v8, v1
	v_mov_b32_e32 v9, v1
	v_mov_b32_e32 v10, v1
	v_mov_b32_e32 v11, v1
	v_mov_b32_e32 v12, v1
	v_mov_b32_e32 v13, v1
	v_mov_b32_e32 v14, v1
	v_mov_b32_e32 v15, v1
	v_mov_b32_e32 v34, 0x42000000
	v_mov_b64_e32 v[32:33], v[16:17]
	s_lshl_b32 s9, s9, 19
	v_lshlrev_b64 v[136:137], 13, v[134:135]
	v_lshlrev_b64 v[138:139], 13, v[132:133]
	s_lshr_b32 s8, s8, 1
	v_lshl_add_u32 v114, v193, 4, v179
	v_lshl_add_u64 v[144:145], s[0:1], 0, v[0:1]
	s_mov_b32 s15, 0
	v_mov_b32_e32 v135, 0xc2000000
	v_mov_b32_e32 v133, 0
	v_mov_b64_e32 v[30:31], v[14:15]
	v_mov_b64_e32 v[28:29], v[12:13]
	v_mov_b64_e32 v[26:27], v[10:11]
	v_mov_b64_e32 v[24:25], v[8:9]
	v_mov_b64_e32 v[22:23], v[6:7]
	v_mov_b64_e32 v[20:21], v[4:5]
	v_mov_b64_e32 v[18:19], v[2:3]
	s_mov_b32 s0, 0
	s_mov_b32 s16, 0
	v_mov_b32_e32 v35, v34
	v_mov_b32_e32 v36, v34
	v_mov_b32_e32 v37, v34
	v_mov_b32_e32 v38, v34
	v_mov_b32_e32 v39, v34
	v_mov_b32_e32 v40, v34
	v_mov_b32_e32 v41, v34
	v_mov_b32_e32 v42, v34
	v_mov_b32_e32 v43, v34
	v_mov_b32_e32 v44, v34
	v_mov_b32_e32 v45, v34
	v_mov_b32_e32 v46, v34
	v_mov_b32_e32 v47, v34
	v_mov_b32_e32 v48, v34
	v_mov_b32_e32 v49, v34
	s_and_b32 s18, s13, 3
	s_lshl_b32 s18, s18, 20
	v_readlane_b32 s12, v234, 54
	v_readlane_b32 s13, v234, 55
	v_readlane_b32 s24, v234, 52
	v_readlane_b32 s25, v234, 53
	s_add_u32 s12, s12, s18
	s_addc_u32 s13, s13, 0
	s_add_u32 s24, s24, s18
	s_addc_u32 s25, s25, 0
	s_add_u32 s12, s12, 0x4000
	s_addc_u32 s13, s13, 0
	s_add_u32 s24, s24, 0x100
	s_addc_u32 s25, s25, 0
	v_lshlrev_b32_e32 v228, 4, v156
	v_lshrrev_b32_e32 v230, 3, v156
	v_and_b32_e32 v231, 7, v156
	v_add_u32_e32 v229, 0x1000, v228
	v_lshlrev_b32_e32 v230, 14, v230
	v_lshl_add_u32 v230, v231, 4, v230
	v_add_u32_e32 v231, 0x80000, v230

.LBB0_907:
	s_add_i32 s1, s16, 2
	s_cmp_gt_u32 s1, s8
	s_cbranch_scc1 .LBB0_909
	global_load_dwordx4 v[98:101], v228, s[12:13]
	global_load_dwordx4 v[102:105], v230, s[24:25]
	global_load_dwordx4 v[106:109], v229, s[12:13]
	global_load_dwordx4 v[110:113], v231, s[24:25]
	s_add_u32 s12, s12, 0x2000
	s_addc_u32 s13, s13, 0
	s_add_u32 s24, s24, 0x80
	s_addc_u32 s25, s25, 0
.LBB0_909:
	s_cmp_gt_i32 s15, s14
	s_waitcnt lgkmcnt(0)
	s_barrier
	s_cbranch_scc1 .LBB0_921
	s_lshr_b32 s1, s16, 3
	s_and_b32 s1, s1, 0x1ffffffc
	v_add_u32_e32 v50, s1, v114
	ds_read_b32 v50, v50
	s_and_b32 s1, s16, 31
	s_waitcnt lgkmcnt(0)
	v_bfe_u32 v51, v50, s1, 1
	v_cmp_ne_u32_e32 vcc, 0, v51
	s_cbranch_vccz .LBB0_921
	s_mul_i32 s22, s0, 0x4a00
	v_add3_u32 v193, s22, v182, v130
	v_lshrrev_b32_e32 v147, s1, v50
	ds_read_b128 v[148:151], v193 offset:4608
	ds_read_b128 v[50:53], v193
	ds_read_b128 v[152:155], v193 offset:32
	s_add_i32 s23, s15, 63
	v_cmp_le_i32_e32 vcc, s23, v128
	s_waitcnt lgkmcnt(1)
	v_mfma_f32_32x32x16_bf16 v[66:81], v[50:53], v[82:85], v[34:49]
	s_waitcnt lgkmcnt(0)
	v_mfma_f32_32x32x16_bf16 v[66:81], v[152:155], v[86:89], v[66:81]
	v_and_b32_e32 v147, 1, v147
	s_cmp_lg_u64 vcc, exec
	s_mov_b64 s[0:1], -1
	v_cmp_eq_u32_e32 vcc, 1, v147
	s_mov_b64 s[4:5], -1
	v_mfma_f32_32x32x16_bf16 v[50:65], v[148:151], v[82:85], v[34:49]
	ds_read_b128 v[148:151], v193 offset:4640
	s_waitcnt lgkmcnt(0)
	v_mfma_f32_32x32x16_bf16 v[50:65], v[148:151], v[86:89], v[50:65]
	ds_read_b128 v[148:151], v193 offset:4672
	ds_read_b128 v[152:155], v193 offset:64
	s_waitcnt lgkmcnt(0)
	v_mfma_f32_32x32x16_bf16 v[66:81], v[152:155], v[90:93], v[66:81]
	v_mfma_f32_32x32x16_bf16 v[50:65], v[148:151], v[90:93], v[50:65]
	ds_read_b128 v[148:151], v193 offset:4704
	ds_read_b128 v[152:155], v193 offset:96
	s_waitcnt lgkmcnt(0)
	v_mfma_f32_32x32x16_bf16 v[66:81], v[152:155], v[94:97], v[66:81]
	v_mfma_f32_32x32x16_bf16 v[50:65], v[148:151], v[94:97], v[50:65]
	s_cbranch_scc0 .LBB0_917
	v_cndmask_b32_e32 v148, -1, v128, vcc
	v_cmp_le_i32_e32 vcc, s23, v148
	s_cmp_eq_u64 vcc, exec
	s_cbranch_scc1 .LBB0_916
	v_add_u32_e32 v149, s15, v125
	v_cmp_lt_i32_e32 vcc, v149, v148
	v_add_u32_e32 v150, 2, v149
	s_nop 2
	v_cndmask_b32_e32 v67, v169, v67, vcc
	v_cmp_le_i32_e32 vcc, v149, v148
	s_nop 1
	v_cndmask_b32_e32 v66, v169, v66, vcc
	v_cmp_le_i32_e32 vcc, v150, v148
	v_add_u32_e32 v150, 3, v149
	s_nop 0
	v_cndmask_b32_e32 v68, v169, v68, vcc
	v_cmp_le_i32_e32 vcc, v150, v148
	v_add_u32_e32 v150, 8, v149
	s_nop 0
	v_cndmask_b32_e32 v69, v169, v69, vcc
	v_cmp_le_i32_e32 vcc, v150, v148
	v_add_u32_e32 v150, 9, v149
	s_nop 0
	v_cndmask_b32_e32 v70, v169, v70, vcc
	v_cmp_le_i32_e32 vcc, v150, v148
	v_add_u32_e32 v150, 10, v149
	s_nop 0
	v_cndmask_b32_e32 v71, v169, v71, vcc
	v_cmp_le_i32_e32 vcc, v150, v148
	v_add_u32_e32 v150, 11, v149
	s_nop 0
	v_cndmask_b32_e32 v72, v169, v72, vcc
	v_cmp_le_i32_e32 vcc, v150, v148
	v_add_u32_e32 v150, 16, v149
	s_nop 0
	v_cndmask_b32_e32 v73, v169, v73, vcc
	v_cmp_le_i32_e32 vcc, v150, v148
	v_add_u32_e32 v150, 17, v149
	s_nop 0
	v_cndmask_b32_e32 v74, v169, v74, vcc
	v_cmp_le_i32_e32 vcc, v150, v148
	v_add_u32_e32 v150, 18, v149
	s_nop 0
	v_cndmask_b32_e32 v75, v169, v75, vcc
	v_cmp_le_i32_e32 vcc, v150, v148
	v_add_u32_e32 v150, 19, v149
	s_nop 0
	v_cndmask_b32_e32 v76, v169, v76, vcc
	v_cmp_le_i32_e32 vcc, v150, v148
	v_add_u32_e32 v150, 24, v149
	s_nop 0
	v_cndmask_b32_e32 v77, v169, v77, vcc
	v_cmp_le_i32_e32 vcc, v150, v148
	v_add_u32_e32 v150, 25, v149
	s_nop 0
	v_cndmask_b32_e32 v78, v169, v78, vcc
	v_cmp_le_i32_e32 vcc, v150, v148
	v_add_u32_e32 v150, 26, v149
	s_nop 0
	v_cndmask_b32_e32 v79, v169, v79, vcc
	v_cmp_le_i32_e32 vcc, v150, v148
	v_add_u32_e32 v150, 27, v149
	s_nop 0
	v_cndmask_b32_e32 v80, v169, v80, vcc
	v_cmp_le_i32_e32 vcc, v150, v148
	v_add_u32_e32 v150, 32, v149
	s_nop 0
	v_cndmask_b32_e32 v81, v169, v81, vcc
	v_cmp_le_i32_e32 vcc, v150, v148
	v_add_u32_e32 v150, 33, v149
	s_nop 0
	v_cndmask_b32_e32 v50, v169, v50, vcc
	v_cmp_le_i32_e32 vcc, v150, v148
	v_add_u32_e32 v150, 34, v149
	s_nop 0
	v_cndmask_b32_e32 v51, v169, v51, vcc
	v_cmp_le_i32_e32 vcc, v150, v148
	v_add_u32_e32 v150, 35, v149
	s_nop 0
	v_cndmask_b32_e32 v52, v169, v52, vcc
	v_cmp_le_i32_e32 vcc, v150, v148
	v_add_u32_e32 v150, 40, v149
	s_nop 0
	v_cndmask_b32_e32 v53, v169, v53, vcc
	v_cmp_le_i32_e32 vcc, v150, v148
	v_add_u32_e32 v150, 41, v149
	s_nop 0
	v_cndmask_b32_e32 v54, v169, v54, vcc
	v_cmp_le_i32_e32 vcc, v150, v148
	v_add_u32_e32 v150, 42, v149
	s_nop 0
	v_cndmask_b32_e32 v55, v169, v55, vcc
	v_cmp_le_i32_e32 vcc, v150, v148
	v_add_u32_e32 v150, 43, v149
	s_nop 0
	v_cndmask_b32_e32 v56, v169, v56, vcc
	v_cmp_le_i32_e32 vcc, v150, v148
	v_add_u32_e32 v150, 48, v149
	s_nop 0
	v_cndmask_b32_e32 v57, v169, v57, vcc
	v_cmp_le_i32_e32 vcc, v150, v148
	v_add_u32_e32 v150, 49, v149
	s_nop 0
	v_cndmask_b32_e32 v58, v169, v58, vcc
	v_cmp_le_i32_e32 vcc, v150, v148
	v_add_u32_e32 v150, 50, v149
	s_nop 0
	v_cndmask_b32_e32 v59, v169, v59, vcc
	v_cmp_le_i32_e32 vcc, v150, v148
	v_add_u32_e32 v150, 51, v149
	s_nop 0
	v_cndmask_b32_e32 v60, v169, v60, vcc
	v_cmp_le_i32_e32 vcc, v150, v148
	v_add_u32_e32 v150, 56, v149
	s_nop 0
	v_cndmask_b32_e32 v61, v169, v61, vcc
	v_cmp_le_i32_e32 vcc, v150, v148
	v_add_u32_e32 v150, 57, v149
	s_nop 0
	v_cndmask_b32_e32 v62, v169, v62, vcc
	v_cmp_le_i32_e32 vcc, v150, v148
	v_add_u32_e32 v150, 58, v149
	v_add_u32_e32 v149, 59, v149
	v_cndmask_b32_e32 v63, v169, v63, vcc
	v_cmp_le_i32_e32 vcc, v150, v148
	s_nop 1
	v_cndmask_b32_e32 v64, v169, v64, vcc
	v_cmp_gt_i32_e32 vcc, v149, v148
	s_and_saveexec_b64 s[4:5], vcc
	v_mov_b32_e32 v65, 0xf149f2ca
	s_or_b64 exec, exec, s[4:5]

.LBB0_926:
	v_mov_b32_e32 v34, 0x42000000
	v_mov_b32_e32 v136, 0
	s_add_i32 s9, s7, 0xfffffdfa
	v_add_u32_e32 v137, 0xfffffe01, v128
	v_lshl_add_u64 v[114:115], s[0:1], 0, v[0:1]
	v_lshl_add_u64 v[132:133], v[2:3], 0, v[0:1]
	v_lshl_add_u64 v[134:135], v[4:5], 0, v[0:1]
	s_lshl_b32 s14, s6, 6
	s_mov_b32 s0, 0
	v_mov_b32_e32 v0, 0xc2000000
	v_mov_b32_e32 v2, 0
	v_mov_b32_e32 v3, v136
	v_mov_b32_e32 v4, v136
	v_mov_b32_e32 v5, v136
	v_mov_b32_e32 v6, v136
	v_mov_b32_e32 v7, v136
	v_mov_b32_e32 v8, v136
	v_mov_b32_e32 v9, v136
	v_mov_b32_e32 v10, v136
	v_mov_b32_e32 v11, v136
	v_mov_b32_e32 v12, v136
	v_mov_b32_e32 v13, v136
	v_mov_b32_e32 v14, v136
	v_mov_b32_e32 v15, v136
	v_mov_b32_e32 v16, v136
	v_mov_b32_e32 v17, v136
	v_mov_b32_e32 v18, 0
	v_mov_b32_e32 v19, v136
	v_mov_b32_e32 v20, v136
	v_mov_b32_e32 v21, v136
	v_mov_b32_e32 v22, v136
	v_mov_b32_e32 v23, v136
	v_mov_b32_e32 v24, v136
	v_mov_b32_e32 v25, v136
	v_mov_b32_e32 v26, v136
	v_mov_b32_e32 v27, v136
	v_mov_b32_e32 v28, v136
	v_mov_b32_e32 v29, v136
	v_mov_b32_e32 v30, v136
	v_mov_b32_e32 v31, v136
	v_mov_b32_e32 v32, v136
	v_mov_b32_e32 v33, v136
	v_mov_b32_e32 v35, v34
	v_mov_b32_e32 v36, v34
	v_mov_b32_e32 v37, v34
	v_mov_b32_e32 v38, v34
	v_mov_b32_e32 v39, v34
	v_mov_b32_e32 v40, v34
	v_mov_b32_e32 v41, v34
	v_mov_b32_e32 v42, v34
	v_mov_b32_e32 v43, v34
	v_mov_b32_e32 v44, v34
	v_mov_b32_e32 v45, v34
	v_mov_b32_e32 v46, v34
	v_mov_b32_e32 v47, v34
	v_mov_b32_e32 v48, v34
	v_mov_b32_e32 v49, v34
	v_readlane_b32 s12, v234, 50
	v_readlane_b32 s13, v234, 51
	v_readlane_b32 s24, v234, 48
	v_readlane_b32 s25, v234, 49
	s_add_u32 s12, s12, s18
	s_addc_u32 s13, s13, 0
	s_add_u32 s24, s24, s18
	s_addc_u32 s25, s25, 0
	s_add_i32 s1, s6, 2
	s_lshl_b32 s16, s1, 13
	s_lshl_b32 s17, s1, 7
	s_add_u32 s12, s12, s16
	s_addc_u32 s13, s13, 0
	s_add_u32 s24, s24, s17
	s_addc_u32 s25, s25, 0

.LBB0_929:
	s_add_i32 s1, s6, 2
	s_cmp_gt_i32 s1, s8
	s_cbranch_scc1 .LBB0_931
	global_load_dwordx4 v[98:101], v228, s[12:13]
	global_load_dwordx4 v[102:105], v230, s[24:25]
	global_load_dwordx4 v[106:109], v229, s[12:13]
	global_load_dwordx4 v[110:113], v231, s[24:25]
	s_add_u32 s12, s12, 0x2000
	s_addc_u32 s13, s13, 0
	s_add_u32 s24, s24, 0x80
	s_addc_u32 s25, s25, 0
.LBB0_931:
	s_cmp_le_i32 s14, s7
	s_cselect_b64 s[16:17], -1, 0
	s_add_i32 s1, s14, 63
	s_cmp_ge_i32 s1, s9
	s_cselect_b64 s[22:23], -1, 0
	s_and_b64 s[16:17], s[16:17], s[22:23]
	s_andn2_b64 vcc, exec, s[16:17]
	s_waitcnt lgkmcnt(0)
	s_barrier
	s_cbranch_vccnz .LBB0_938
	s_mul_i32 s16, s0, 0x4a00
	v_add3_u32 v142, s16, v182, v130
	ds_read_b128 v[50:53], v142
	ds_read_b128 v[138:141], v142 offset:4608
	v_cmp_le_i32_e32 vcc, s1, v128
	v_cmp_ge_i32_e64 s[0:1], s14, v137
	s_and_b64 s[0:1], vcc, s[0:1]
	s_waitcnt lgkmcnt(1)
	v_mfma_f32_32x32x16_bf16 v[66:81], v[50:53], v[82:85], v[34:49]
	s_waitcnt lgkmcnt(0)
	v_mfma_f32_32x32x16_bf16 v[50:65], v[138:141], v[82:85], v[34:49]
	ds_read_b128 v[138:141], v142 offset:32
	s_waitcnt lgkmcnt(0)
	v_mfma_f32_32x32x16_bf16 v[66:81], v[138:141], v[86:89], v[66:81]
	ds_read_b128 v[138:141], v142 offset:4640
	s_waitcnt lgkmcnt(0)
	v_mfma_f32_32x32x16_bf16 v[50:65], v[138:141], v[86:89], v[50:65]
	ds_read_b128 v[138:141], v142 offset:64
	s_waitcnt lgkmcnt(0)
	v_mfma_f32_32x32x16_bf16 v[66:81], v[138:141], v[90:93], v[66:81]
	ds_read_b128 v[138:141], v142 offset:4672
	s_waitcnt lgkmcnt(0)
	v_mfma_f32_32x32x16_bf16 v[50:65], v[138:141], v[90:93], v[50:65]
	ds_read_b128 v[138:141], v142 offset:96
	s_waitcnt lgkmcnt(0)
	v_mfma_f32_32x32x16_bf16 v[66:81], v[138:141], v[94:97], v[66:81]
	ds_read_b128 v[138:141], v142 offset:4704
	v_cndmask_b32_e64 v142, 0, 1, s[0:1]
	v_cmp_ne_u32_e32 vcc, 0, v142
	s_cmp_eq_u64 vcc, exec
	s_waitcnt lgkmcnt(0)
	v_mfma_f32_32x32x16_bf16 v[50:65], v[138:141], v[94:97], v[50:65]
	s_cbranch_scc1 .LBB0_936
	v_add_u32_e32 v138, s14, v125
	v_cmp_gt_i32_e32 vcc, v138, v128
	v_cmp_lt_i32_e64 s[0:1], v138, v137
	s_or_b64 vcc, vcc, s[0:1]
	v_add_u32_e32 v139, 1, v138
	v_cndmask_b32_e32 v66, v66, v169, vcc
	v_cmp_ge_i32_e32 vcc, v138, v128
	v_cmp_lt_i32_e64 s[0:1], v139, v137
	s_or_b64 vcc, vcc, s[0:1]
	v_add_u32_e32 v139, 2, v138
	v_cndmask_b32_e32 v67, v67, v169, vcc
	v_cmp_gt_i32_e32 vcc, v139, v128
	v_cmp_lt_i32_e64 s[0:1], v139, v137
	s_or_b64 vcc, vcc, s[0:1]
	v_add_u32_e32 v139, 3, v138
	v_cndmask_b32_e32 v68, v68, v169, vcc
	v_cmp_gt_i32_e32 vcc, v139, v128
	v_cmp_lt_i32_e64 s[0:1], v139, v137
	s_or_b64 vcc, vcc, s[0:1]
	v_add_u32_e32 v139, 8, v138
	v_cndmask_b32_e32 v69, v69, v169, vcc
	v_cmp_gt_i32_e32 vcc, v139, v128
	v_cmp_lt_i32_e64 s[0:1], v139, v137
	s_or_b64 vcc, vcc, s[0:1]
	v_add_u32_e32 v139, 9, v138
	v_cndmask_b32_e32 v70, v70, v169, vcc
	v_cmp_gt_i32_e32 vcc, v139, v128
	v_cmp_lt_i32_e64 s[0:1], v139, v137
	s_or_b64 vcc, vcc, s[0:1]
	v_add_u32_e32 v139, 10, v138
	v_cndmask_b32_e32 v71, v71, v169, vcc
	v_cmp_gt_i32_e32 vcc, v139, v128
	v_cmp_lt_i32_e64 s[0:1], v139, v137
	s_or_b64 vcc, vcc, s[0:1]
	v_add_u32_e32 v139, 11, v138
	v_cndmask_b32_e32 v72, v72, v169, vcc
	v_cmp_gt_i32_e32 vcc, v139, v128
	v_cmp_lt_i32_e64 s[0:1], v139, v137
	s_or_b64 vcc, vcc, s[0:1]
	v_add_u32_e32 v139, 16, v138
	v_cndmask_b32_e32 v73, v73, v169, vcc
	v_cmp_gt_i32_e32 vcc, v139, v128
	v_cmp_lt_i32_e64 s[0:1], v139, v137
	s_or_b64 vcc, vcc, s[0:1]
	v_add_u32_e32 v139, 17, v138
	v_cndmask_b32_e32 v74, v74, v169, vcc
	v_cmp_gt_i32_e32 vcc, v139, v128
	v_cmp_lt_i32_e64 s[0:1], v139, v137
	s_or_b64 vcc, vcc, s[0:1]
	v_add_u32_e32 v139, 18, v138
	v_cndmask_b32_e32 v75, v75, v169, vcc
	v_cmp_gt_i32_e32 vcc, v139, v128
	v_cmp_lt_i32_e64 s[0:1], v139, v137
	s_or_b64 vcc, vcc, s[0:1]
	v_add_u32_e32 v139, 19, v138
	v_cndmask_b32_e32 v76, v76, v169, vcc
	v_cmp_gt_i32_e32 vcc, v139, v128
	v_cmp_lt_i32_e64 s[0:1], v139, v137
	s_or_b64 vcc, vcc, s[0:1]
	v_add_u32_e32 v139, 24, v138
	v_cndmask_b32_e32 v77, v77, v169, vcc
	v_cmp_gt_i32_e32 vcc, v139, v128
	v_cmp_lt_i32_e64 s[0:1], v139, v137
	s_or_b64 vcc, vcc, s[0:1]
	v_add_u32_e32 v139, 25, v138
	v_cndmask_b32_e32 v78, v78, v169, vcc
	v_cmp_gt_i32_e32 vcc, v139, v128
	v_cmp_lt_i32_e64 s[0:1], v139, v137
	s_or_b64 vcc, vcc, s[0:1]
	v_add_u32_e32 v139, 26, v138
	v_cndmask_b32_e32 v79, v79, v169, vcc
	v_cmp_gt_i32_e32 vcc, v139, v128
	v_cmp_lt_i32_e64 s[0:1], v139, v137
	s_or_b64 vcc, vcc, s[0:1]
	v_add_u32_e32 v139, 27, v138
	v_cndmask_b32_e32 v80, v80, v169, vcc
	v_cmp_gt_i32_e32 vcc, v139, v128
	v_cmp_lt_i32_e64 s[0:1], v139, v137
	s_or_b64 vcc, vcc, s[0:1]
	v_add_u32_e32 v139, 32, v138
	v_cndmask_b32_e32 v81, v81, v169, vcc
	v_cmp_gt_i32_e32 vcc, v139, v128
	v_cmp_lt_i32_e64 s[0:1], v139, v137
	s_or_b64 vcc, vcc, s[0:1]
	v_add_u32_e32 v139, 33, v138
	v_cndmask_b32_e32 v50, v50, v169, vcc
	v_cmp_gt_i32_e32 vcc, v139, v128
	v_cmp_lt_i32_e64 s[0:1], v139, v137
	s_or_b64 vcc, vcc, s[0:1]
	v_add_u32_e32 v139, 34, v138
	v_cndmask_b32_e32 v51, v51, v169, vcc
	v_cmp_gt_i32_e32 vcc, v139, v128
	v_cmp_lt_i32_e64 s[0:1], v139, v137
	s_or_b64 vcc, vcc, s[0:1]
	v_add_u32_e32 v139, 35, v138
	v_cndmask_b32_e32 v52, v52, v169, vcc
	v_cmp_gt_i32_e32 vcc, v139, v128
	v_cmp_lt_i32_e64 s[0:1], v139, v137
	s_or_b64 vcc, vcc, s[0:1]
	v_add_u32_e32 v139, 40, v138
	v_cndmask_b32_e32 v53, v53, v169, vcc
	v_cmp_gt_i32_e32 vcc, v139, v128
	v_cmp_lt_i32_e64 s[0:1], v139, v137
	s_or_b64 vcc, vcc, s[0:1]
	v_add_u32_e32 v139, 41, v138
	v_cndmask_b32_e32 v54, v54, v169, vcc
	v_cmp_gt_i32_e32 vcc, v139, v128
	v_cmp_lt_i32_e64 s[0:1], v139, v137
	s_or_b64 vcc, vcc, s[0:1]
	v_add_u32_e32 v139, 42, v138
	v_cndmask_b32_e32 v55, v55, v169, vcc
	v_cmp_gt_i32_e32 vcc, v139, v128
	v_cmp_lt_i32_e64 s[0:1], v139, v137
	s_or_b64 vcc, vcc, s[0:1]
	v_add_u32_e32 v139, 43, v138
	v_cndmask_b32_e32 v56, v56, v169, vcc
	v_cmp_gt_i32_e32 vcc, v139, v128
	v_cmp_lt_i32_e64 s[0:1], v139, v137
	s_or_b64 vcc, vcc, s[0:1]
	v_add_u32_e32 v139, 48, v138
	v_cndmask_b32_e32 v57, v57, v169, vcc
	v_cmp_gt_i32_e32 vcc, v139, v128
	v_cmp_lt_i32_e64 s[0:1], v139, v137
	s_or_b64 vcc, vcc, s[0:1]
	v_add_u32_e32 v139, 49, v138
	v_cndmask_b32_e32 v58, v58, v169, vcc
	v_cmp_gt_i32_e32 vcc, v139, v128
	v_cmp_lt_i32_e64 s[0:1], v139, v137
	s_or_b64 vcc, vcc, s[0:1]
	v_add_u32_e32 v139, 50, v138
	v_cndmask_b32_e32 v59, v59, v169, vcc
	v_cmp_gt_i32_e32 vcc, v139, v128
	v_cmp_lt_i32_e64 s[0:1], v139, v137
	s_or_b64 vcc, vcc, s[0:1]
	v_add_u32_e32 v139, 51, v138
	v_cndmask_b32_e32 v60, v60, v169, vcc
	v_cmp_gt_i32_e32 vcc, v139, v128
	v_cmp_lt_i32_e64 s[0:1], v139, v137
	s_or_b64 vcc, vcc, s[0:1]
	v_add_u32_e32 v139, 56, v138
	v_cndmask_b32_e32 v61, v61, v169, vcc
	v_cmp_gt_i32_e32 vcc, v139, v128
	v_cmp_lt_i32_e64 s[0:1], v139, v137
	s_or_b64 vcc, vcc, s[0:1]
	v_add_u32_e32 v139, 57, v138
	v_cndmask_b32_e32 v62, v62, v169, vcc
	v_cmp_gt_i32_e32 vcc, v139, v128
	v_cmp_lt_i32_e64 s[0:1], v139, v137
	s_or_b64 vcc, vcc, s[0:1]
	v_add_u32_e32 v139, 58, v138
	v_cndmask_b32_e32 v63, v63, v169, vcc
	v_cmp_gt_i32_e32 vcc, v139, v128
	v_cmp_lt_i32_e64 s[0:1], v139, v137
	s_or_b64 vcc, vcc, s[0:1]
	v_add_u32_e32 v138, 59, v138
	v_cndmask_b32_e32 v64, v64, v169, vcc
	v_cmp_gt_i32_e32 vcc, v138, v128
	v_cmp_lt_i32_e64 s[0:1], v138, v137
	s_or_b64 s[22:23], vcc, s[0:1]
	s_and_saveexec_b64 s[0:1], s[22:23]
	v_mov_b32_e32 v65, 0xf149f2ca
	s_or_b64 exec, exec, s[0:1]
